# loop-edge rotation on 20 GEMM K-loops as v74, each insertion padded to 128 B with never-executed s_nop so that every loop head and all later code keep v67's addresses mod 128
# baseline (speedup 1.0000x reference)
; template <class Epi, class Sched, bool ALIGN_EPI = false, bool SP2 = false>
; __device__ __forceinline__ void gemm_phase(PG8_LAS unsigned char* lds, const Gemm g, const Sched& S, const Epi& E, const int wid  ) {
;     ...
;         const bool has_next = S.next(ui + 1, nxt); nxt.same = (has_next && nxt.pm == cur.pm) ? 1 : 0;
;         const unsigned nA = has_next ? (unsigned)g.asel(nxt.pn) * (unsigned)g.a_stride + (unsigned)nxt.pm * tstep : cA, nB = has_next ? (unsigned)nxt.pn * tstep : cB;
;         for (int t = 0; t < nt; t += 2) {
;             const bool last = (t == nt - 2);
;             const unsigned a1 = cA + (unsigned)(t + 1) * kstep;
;             const unsigned a2 = last ? nA : cA + (unsigned)(t + 2) * kstep, b2 = last ? nB : cB + (unsigned)(t + 2) * kstep;
;             const unsigned a3 = a2 + kstep, b3 = b2 + kstep;
;     ...
; #pragma unroll
;         for (int a = 0; a < 2; ++a)
; #pragma unroll
;             for (int b = 0; b < 2; ++b)
; #pragma unroll
;                 for (int m = 0; m < 4; ++m)
; #pragma unroll
;                     for (int n = 0; n < 2; ++n) acc[a][b][m][n] = (f32x4){0.f, 0.f, 0.f, 0.f};
;         cur = nxt; cA = nA; cB = nB; ++ui;
.LBB0_203:
	s_lshl_b32 s60, s59, 20
	s_and_b64 s[14:15], s[4:5], exec
	s_cselect_b32 s63, s60, s65
	s_lshl_b32 s61, s58, 20
	s_and_b64 s[14:15], s[4:5], exec
	v_mov_b32_e32 v0, 0
	s_cselect_b32 s64, s61, s66
	s_add_i32 s65, s65, 0x80080
	s_addk_i32 s66, 0x100
	s_mov_b32 s67, -2
	v_mov_b32_e32 v1, v0
	s_waitcnt lgkmcnt(7)
	v_mov_b32_e32 v2, v0
	v_mov_b32_e32 v3, v0
	s_waitcnt lgkmcnt(6)
	v_mov_b32_e32 v4, v0
	v_mov_b32_e32 v5, v0
	s_waitcnt lgkmcnt(5)
	v_mov_b32_e32 v6, v0
	v_mov_b32_e32 v7, v0
	s_waitcnt lgkmcnt(2)
	v_mov_b32_e32 v12, v0
	v_mov_b32_e32 v13, v0
	s_waitcnt lgkmcnt(1)
	v_mov_b32_e32 v14, v0
	v_mov_b32_e32 v15, v0
	v_mov_b32_e32 v20, v0
	v_mov_b32_e32 v21, v0
	v_mov_b32_e32 v22, v0
	v_mov_b32_e32 v23, v0
	v_mov_b32_e32 v28, v0
	v_mov_b32_e32 v29, v0
	v_mov_b32_e32 v30, v0
	v_mov_b32_e32 v31, v0
	v_mov_b32_e32 v36, v0
	v_mov_b32_e32 v37, v0
	v_mov_b32_e32 v38, v0
	v_mov_b32_e32 v39, v0
	v_mov_b32_e32 v44, v0
	v_mov_b32_e32 v45, v0
	v_mov_b32_e32 v46, v0
	v_mov_b32_e32 v47, v0
	v_mov_b32_e32 v52, v0
	v_mov_b32_e32 v53, v0
	v_mov_b32_e32 v54, v0
	v_mov_b32_e32 v55, v0
	v_mov_b32_e32 v8, v0
	v_mov_b32_e32 v9, v0
	v_mov_b32_e32 v10, v0
	v_mov_b32_e32 v11, v0
	s_waitcnt lgkmcnt(0)
	v_mov_b32_e32 v16, v0
	v_mov_b32_e32 v17, v0
	s_waitcnt lgkmcnt(0)
	v_mov_b32_e32 v18, v0
	v_mov_b32_e32 v19, v0
	v_mov_b32_e32 v24, v0
	v_mov_b32_e32 v25, v0
	v_mov_b32_e32 v26, v0
	v_mov_b32_e32 v27, v0
	v_mov_b32_e32 v32, v0
	v_mov_b32_e32 v33, v0
	v_mov_b32_e32 v34, v0
	v_mov_b32_e32 v35, v0
	v_mov_b32_e32 v40, v0
	v_mov_b32_e32 v41, v0
	v_mov_b32_e32 v42, v0
	v_mov_b32_e32 v43, v0
	v_mov_b32_e32 v48, v0
	v_mov_b32_e32 v49, v0
	v_mov_b32_e32 v50, v0
	v_mov_b32_e32 v51, v0
	v_mov_b32_e32 v56, v0
	v_mov_b32_e32 v57, v0
	v_mov_b32_e32 v58, v0
	v_mov_b32_e32 v59, v0
	v_mov_b32_e32 v60, v0
	v_mov_b32_e32 v61, v0
	v_mov_b32_e32 v62, v0
	v_mov_b32_e32 v63, v0
	v_mov_b32_e32 v64, v0
	v_mov_b32_e32 v65, v0
	v_mov_b32_e32 v66, v0
	v_mov_b32_e32 v67, v0
	v_mov_b32_e32 v68, v0
	v_mov_b32_e32 v69, v0
	v_mov_b32_e32 v70, v0
	v_mov_b32_e32 v71, v0
	v_mov_b32_e32 v76, v0
	v_mov_b32_e32 v77, v0
	v_mov_b32_e32 v78, v0
	v_mov_b32_e32 v79, v0
	v_mov_b32_e32 v84, v0
	v_mov_b32_e32 v85, v0
	v_mov_b32_e32 v86, v0
	v_mov_b32_e32 v87, v0
	v_mov_b32_e32 v92, v0
	v_mov_b32_e32 v93, v0
	v_mov_b32_e32 v94, v0
	v_mov_b32_e32 v95, v0
	v_mov_b32_e32 v100, v0
	v_mov_b32_e32 v101, v0
	v_mov_b32_e32 v102, v0
	v_mov_b32_e32 v103, v0
	v_mov_b32_e32 v108, v0
	v_mov_b32_e32 v109, v0
	v_mov_b32_e32 v110, v0
	v_mov_b32_e32 v111, v0
	v_mov_b32_e32 v116, v0
	v_mov_b32_e32 v117, v0
	v_mov_b32_e32 v118, v0
	v_mov_b32_e32 v119, v0
	v_mov_b32_e32 v72, v0
	v_mov_b32_e32 v73, v0
	v_mov_b32_e32 v74, v0
	v_mov_b32_e32 v75, v0
	v_mov_b32_e32 v80, v0
	v_mov_b32_e32 v81, v0
	v_mov_b32_e32 v82, v0
	v_mov_b32_e32 v83, v0
	v_mov_b32_e32 v88, v0
	v_mov_b32_e32 v89, v0
	v_mov_b32_e32 v90, v0
	v_mov_b32_e32 v91, v0
	v_mov_b32_e32 v96, v0
	v_mov_b32_e32 v97, v0
	v_mov_b32_e32 v98, v0
	v_mov_b32_e32 v99, v0
	v_mov_b32_e32 v104, v0
	v_mov_b32_e32 v105, v0
	v_mov_b32_e32 v106, v0
	v_mov_b32_e32 v107, v0
	v_mov_b32_e32 v112, v0
	v_mov_b32_e32 v113, v0
	v_mov_b32_e32 v114, v0
	v_mov_b32_e32 v115, v0
	v_mov_b32_e32 v120, v0
	v_mov_b32_e32 v121, v0
	v_mov_b32_e32 v122, v0
	v_mov_b32_e32 v123, v0
	v_mov_b32_e32 v124, v0
	v_mov_b32_e32 v125, v0
	v_mov_b32_e32 v126, v0
	v_mov_b32_e32 v127, v0
	s_branch .LBB0_204
	s_nop 0
	s_nop 0
	s_nop 0
	s_nop 0
	s_nop 0
	s_nop 0
	s_nop 0
	s_nop 0
	s_nop 0
	s_nop 0
	s_nop 0
	s_nop 0
	s_nop 0
	s_nop 0
	s_nop 0
	s_nop 0
	s_nop 0
	s_nop 0
	s_nop 0
	s_nop 0
	s_nop 0
	s_nop 0
	s_nop 0
	s_nop 0
	s_nop 0
	s_nop 0
	s_nop 0
	s_nop 0
	s_nop 0
	s_nop 0

; template <class Epi, class Sched, bool ALIGN_EPI = false, bool SP2 = false>
; __device__ __forceinline__ void gemm_phase(PG8_LAS unsigned char* lds, const Gemm g, const Sched& S, const Epi& E, const int wid  ) {
;     ...
;         const bool has_next = S.next(ui + 1, nxt); nxt.same = (has_next && nxt.pm == cur.pm) ? 1 : 0;
;         const unsigned nA = has_next ? (unsigned)g.asel(nxt.pn) * (unsigned)g.a_stride + (unsigned)nxt.pm * tstep : cA, nB = has_next ? (unsigned)nxt.pn * tstep : cB;
;         for (int t = 0; t < nt; t += 2) {
;             const bool last = (t == nt - 2);
;             const unsigned a1 = cA + (unsigned)(t + 1) * kstep;
;             const unsigned a2 = last ? nA : cA + (unsigned)(t + 2) * kstep, b2 = last ? nB : cB + (unsigned)(t + 2) * kstep;
;             const unsigned a3 = a2 + kstep, b3 = b2 + kstep;
;     ...
; #pragma unroll
;         for (int a = 0; a < 2; ++a)
; #pragma unroll
;             for (int b = 0; b < 2; ++b)
; #pragma unroll
;                 for (int m = 0; m < 4; ++m)
; #pragma unroll
;                     for (int n = 0; n < 2; ++n) acc[a][b][m][n] = (f32x4){0.f, 0.f, 0.f, 0.f};
;         cur = nxt; cA = nA; cB = nB; ++ui;
.LBB0_563:
	s_lshl_b32 s50, s49, 20
	s_and_b64 s[0:1], s[4:5], exec
	s_cselect_b32 s0, s50, s54
	s_lshl_b32 s51, s48, 20
	s_and_b64 s[14:15], s[4:5], exec
	v_mov_b32_e32 v0, 0
	s_cselect_b32 s1, s51, s55
	s_add_i32 s54, s54, 0x80080
	s_addk_i32 s55, 0x100
	s_mov_b32 s58, -2
	s_waitcnt lgkmcnt(0)
	v_mov_b32_e32 v1, v0
	v_mov_b32_e32 v2, v0
	v_mov_b32_e32 v3, v0
	v_mov_b32_e32 v4, v0
	v_mov_b32_e32 v5, v0
	v_mov_b32_e32 v6, v0
	v_mov_b32_e32 v7, v0
	v_mov_b32_e32 v16, v0
	v_mov_b32_e32 v17, v0
	v_mov_b32_e32 v18, v0
	v_mov_b32_e32 v19, v0
	v_mov_b32_e32 v20, v0
	v_mov_b32_e32 v21, v0
	v_mov_b32_e32 v22, v0
	v_mov_b32_e32 v23, v0
	v_mov_b32_e32 v32, v0
	v_mov_b32_e32 v33, v0
	v_mov_b32_e32 v34, v0
	v_mov_b32_e32 v35, v0
	v_mov_b32_e32 v36, v0
	v_mov_b32_e32 v37, v0
	v_mov_b32_e32 v38, v0
	v_mov_b32_e32 v39, v0
	v_mov_b32_e32 v48, v0
	v_mov_b32_e32 v49, v0
	v_mov_b32_e32 v50, v0
	v_mov_b32_e32 v51, v0
	v_mov_b32_e32 v52, v0
	v_mov_b32_e32 v53, v0
	v_mov_b32_e32 v54, v0
	v_mov_b32_e32 v55, v0
	v_mov_b32_e32 v8, v0
	v_mov_b32_e32 v9, v0
	v_mov_b32_e32 v10, v0
	v_mov_b32_e32 v11, v0
	v_mov_b32_e32 v12, v0
	v_mov_b32_e32 v13, v0
	v_mov_b32_e32 v14, v0
	v_mov_b32_e32 v15, v0
	v_mov_b32_e32 v24, v0
	v_mov_b32_e32 v25, v0
	v_mov_b32_e32 v26, v0
	v_mov_b32_e32 v27, v0
	v_mov_b32_e32 v28, v0
	v_mov_b32_e32 v29, v0
	v_mov_b32_e32 v30, v0
	v_mov_b32_e32 v31, v0
	v_mov_b32_e32 v40, v0
	v_mov_b32_e32 v41, v0
	v_mov_b32_e32 v42, v0
	v_mov_b32_e32 v43, v0
	v_mov_b32_e32 v44, v0
	v_mov_b32_e32 v45, v0
	v_mov_b32_e32 v46, v0
	v_mov_b32_e32 v47, v0
	v_mov_b32_e32 v56, v0
	v_mov_b32_e32 v57, v0
	v_mov_b32_e32 v58, v0
	v_mov_b32_e32 v59, v0
	v_mov_b32_e32 v60, v0
	v_mov_b32_e32 v61, v0
	v_mov_b32_e32 v62, v0
	v_mov_b32_e32 v63, v0
	v_mov_b32_e32 v64, v0
	v_mov_b32_e32 v65, v0
	v_mov_b32_e32 v66, v0
	v_mov_b32_e32 v67, v0
	v_mov_b32_e32 v68, v0
	v_mov_b32_e32 v69, v0
	v_mov_b32_e32 v70, v0
	v_mov_b32_e32 v71, v0
	v_mov_b32_e32 v80, v0
	v_mov_b32_e32 v81, v0
	v_mov_b32_e32 v82, v0
	v_mov_b32_e32 v83, v0
	v_mov_b32_e32 v84, v0
	v_mov_b32_e32 v85, v0
	v_mov_b32_e32 v86, v0
	v_mov_b32_e32 v87, v0
	v_mov_b32_e32 v96, v0
	v_mov_b32_e32 v97, v0
	v_mov_b32_e32 v98, v0
	v_mov_b32_e32 v99, v0
	v_mov_b32_e32 v100, v0
	v_mov_b32_e32 v101, v0
	v_mov_b32_e32 v102, v0
	v_mov_b32_e32 v103, v0
	v_mov_b32_e32 v112, v0
	v_mov_b32_e32 v113, v0
	v_mov_b32_e32 v114, v0
	v_mov_b32_e32 v115, v0
	v_mov_b32_e32 v116, v0
	v_mov_b32_e32 v117, v0
	v_mov_b32_e32 v118, v0
	v_mov_b32_e32 v119, v0
	v_mov_b32_e32 v72, v0
	v_mov_b32_e32 v73, v0
	v_mov_b32_e32 v74, v0
	v_mov_b32_e32 v75, v0
	v_mov_b32_e32 v76, v0
	v_mov_b32_e32 v77, v0
	v_mov_b32_e32 v78, v0
	v_mov_b32_e32 v79, v0
	v_mov_b32_e32 v88, v0
	v_mov_b32_e32 v89, v0
	v_mov_b32_e32 v90, v0
	v_mov_b32_e32 v91, v0
	v_mov_b32_e32 v92, v0
	v_mov_b32_e32 v93, v0
	v_mov_b32_e32 v94, v0
	v_mov_b32_e32 v95, v0
	v_mov_b32_e32 v104, v0
	v_mov_b32_e32 v105, v0
	v_mov_b32_e32 v106, v0
	v_mov_b32_e32 v107, v0
	v_mov_b32_e32 v108, v0
	v_mov_b32_e32 v109, v0
	v_mov_b32_e32 v110, v0
	v_mov_b32_e32 v111, v0
	v_mov_b32_e32 v120, v0
	v_mov_b32_e32 v121, v0
	v_mov_b32_e32 v122, v0
	v_mov_b32_e32 v123, v0
	v_mov_b32_e32 v124, v0
	v_mov_b32_e32 v125, v0
	v_mov_b32_e32 v126, v0
	v_mov_b32_e32 v127, v0
	s_branch .LBB0_564
	s_nop 0
	s_nop 0
	s_nop 0
	s_nop 0
	s_nop 0
	s_nop 0
	s_nop 0
	s_nop 0
	s_nop 0
	s_nop 0
	s_nop 0
	s_nop 0
	s_nop 0
	s_nop 0
	s_nop 0
	s_nop 0
	s_nop 0
	s_nop 0
	s_nop 0
	s_nop 0
	s_nop 0
	s_nop 0
	s_nop 0
	s_nop 0
	s_nop 0
	s_nop 0
	s_nop 0
	s_nop 0
	s_nop 0
	s_nop 0

; template <class Epi, class Sched, bool ALIGN_EPI = false, bool SP2 = false>
; __device__ __forceinline__ void gemm_phase(PG8_LAS unsigned char* lds, const Gemm g, const Sched& S, const Epi& E, const int wid  ) {
;     ...
;         const bool has_next = S.next(ui + 1, nxt); nxt.same = (has_next && nxt.pm == cur.pm) ? 1 : 0;
;         const unsigned nA = has_next ? (unsigned)g.asel(nxt.pn) * (unsigned)g.a_stride + (unsigned)nxt.pm * tstep : cA, nB = has_next ? (unsigned)nxt.pn * tstep : cB;
;         for (int t = 0; t < nt; t += 2) {
;             const bool last = (t == nt - 2);
;             const unsigned a1 = cA + (unsigned)(t + 1) * kstep;
;             const unsigned a2 = last ? nA : cA + (unsigned)(t + 2) * kstep, b2 = last ? nB : cB + (unsigned)(t + 2) * kstep;
;             const unsigned a3 = a2 + kstep, b3 = b2 + kstep;
;     ...
; #pragma unroll
;         for (int a = 0; a < 2; ++a)
; #pragma unroll
;             for (int b = 0; b < 2; ++b)
; #pragma unroll
;                 for (int m = 0; m < 4; ++m)
; #pragma unroll
;                     for (int n = 0; n < 2; ++n) acc[a][b][m][n] = (f32x4){0.f, 0.f, 0.f, 0.f};
;         cur = nxt; cA = nA; cB = nB; ++ui;
.LBB0_657:
	s_lshl_b32 s91, s90, 20
	s_and_b64 s[6:7], s[4:5], exec
	s_cselect_b32 s6, s91, s8
	s_lshl_b32 s92, s89, 20
	s_and_b64 s[18:19], s[4:5], exec
	v_mov_b32_e32 v56, 0
	s_cselect_b32 s7, s92, s9
	s_add_i32 s8, s8, 0x80080
	s_addk_i32 s9, 0x100
	s_mov_b32 s46, -2
	v_mov_b32_e32 v57, v56
	v_mov_b32_e32 v58, v56
	v_mov_b32_e32 v59, v56
	v_mov_b32_e32 v60, v56
	v_mov_b32_e32 v61, v56
	v_mov_b32_e32 v62, v56
	v_mov_b32_e32 v63, v56
	v_mov_b32_e32 v64, v56
	v_mov_b32_e32 v65, v56
	v_mov_b32_e32 v66, v56
	v_mov_b32_e32 v67, v56
	v_mov_b32_e32 v68, v56
	v_mov_b32_e32 v69, v56
	v_mov_b32_e32 v70, v56
	v_mov_b32_e32 v71, v56
	v_mov_b32_e32 v72, v56
	v_mov_b32_e32 v73, v56
	v_mov_b32_e32 v74, v56
	v_mov_b32_e32 v75, v56
	v_mov_b32_e32 v80, v56
	v_mov_b32_e32 v81, v56
	v_mov_b32_e32 v82, v56
	v_mov_b32_e32 v83, v56
	v_mov_b32_e32 v0, v56
	v_mov_b32_e32 v1, v56
	s_waitcnt lgkmcnt(7)
	v_mov_b32_e32 v2, v56
	v_mov_b32_e32 v3, v56
	s_waitcnt lgkmcnt(6)
	v_mov_b32_e32 v4, v56
	v_mov_b32_e32 v5, v56
	s_waitcnt lgkmcnt(5)
	v_mov_b32_e32 v6, v56
	v_mov_b32_e32 v7, v56
	v_mov_b32_e32 v48, v56
	v_mov_b32_e32 v49, v56
	v_mov_b32_e32 v50, v56
	v_mov_b32_e32 v51, v56
	v_mov_b32_e32 v92, v56
	v_mov_b32_e32 v93, v56
	v_mov_b32_e32 v94, v56
	v_mov_b32_e32 v95, v56
	v_mov_b32_e32 v76, v56
	v_mov_b32_e32 v77, v56
	v_mov_b32_e32 v78, v56
	v_mov_b32_e32 v79, v56
	v_mov_b32_e32 v84, v56
	v_mov_b32_e32 v85, v56
	v_mov_b32_e32 v86, v56
	v_mov_b32_e32 v87, v56
	v_mov_b32_e32 v88, v56
	v_mov_b32_e32 v89, v56
	v_mov_b32_e32 v90, v56
	v_mov_b32_e32 v91, v56
	v_mov_b32_e32 v96, v56
	v_mov_b32_e32 v97, v56
	v_mov_b32_e32 v98, v56
	v_mov_b32_e32 v99, v56
	v_mov_b32_e32 v100, v56
	v_mov_b32_e32 v101, v56
	v_mov_b32_e32 v102, v56
	v_mov_b32_e32 v103, v56
	v_mov_b32_e32 v104, v56
	v_mov_b32_e32 v105, v56
	v_mov_b32_e32 v106, v56
	v_mov_b32_e32 v107, v56
	v_mov_b32_e32 v108, v56
	v_mov_b32_e32 v109, v56
	v_mov_b32_e32 v110, v56
	v_mov_b32_e32 v111, v56
	v_mov_b32_e32 v112, v56
	v_mov_b32_e32 v113, v56
	v_mov_b32_e32 v114, v56
	v_mov_b32_e32 v115, v56
	v_mov_b32_e32 v116, v56
	v_mov_b32_e32 v117, v56
	v_mov_b32_e32 v118, v56
	v_mov_b32_e32 v119, v56
	v_mov_b32_e32 v124, v56
	v_mov_b32_e32 v125, v56
	v_mov_b32_e32 v126, v56
	v_mov_b32_e32 v127, v56
	v_mov_b32_e32 v128, v56
	v_mov_b32_e32 v129, v56
	v_mov_b32_e32 v130, v56
	v_mov_b32_e32 v131, v56
	v_mov_b32_e32 v136, v56
	v_mov_b32_e32 v137, v56
	v_mov_b32_e32 v138, v56
	v_mov_b32_e32 v139, v56
	s_waitcnt lgkmcnt(4)
	v_mov_b32_e32 v8, v56
	v_mov_b32_e32 v9, v56
	s_waitcnt lgkmcnt(3)
	v_mov_b32_e32 v10, v56
	v_mov_b32_e32 v11, v56
	s_waitcnt lgkmcnt(2)
	v_mov_b32_e32 v12, v56
	v_mov_b32_e32 v13, v56
	s_waitcnt lgkmcnt(1)
	v_mov_b32_e32 v14, v56
	v_mov_b32_e32 v15, v56
	v_mov_b32_e32 v120, v56
	v_mov_b32_e32 v121, v56
	v_mov_b32_e32 v122, v56
	v_mov_b32_e32 v123, v56
	v_mov_b32_e32 v156, v56
	v_mov_b32_e32 v157, v56
	v_mov_b32_e32 v158, v56
	v_mov_b32_e32 v159, v56
	v_mov_b32_e32 v132, v56
	v_mov_b32_e32 v133, v56
	v_mov_b32_e32 v134, v56
	v_mov_b32_e32 v135, v56
	v_mov_b32_e32 v140, v56
	v_mov_b32_e32 v141, v56
	v_mov_b32_e32 v142, v56
	v_mov_b32_e32 v143, v56
	v_mov_b32_e32 v144, v56
	v_mov_b32_e32 v145, v56
	v_mov_b32_e32 v146, v56
	v_mov_b32_e32 v147, v56
	v_mov_b32_e32 v148, v56
	v_mov_b32_e32 v149, v56
	v_mov_b32_e32 v150, v56
	v_mov_b32_e32 v151, v56
	v_mov_b32_e32 v52, v56
	v_mov_b32_e32 v53, v56
	v_mov_b32_e32 v54, v56
	v_mov_b32_e32 v55, v56
	v_mov_b32_e32 v152, v56
	v_mov_b32_e32 v153, v56
	v_mov_b32_e32 v154, v56
	v_mov_b32_e32 v155, v56
	s_branch .LBB0_658
	s_nop 0
	s_nop 0
	s_nop 0
	s_nop 0
	s_nop 0
	s_nop 0
	s_nop 0
	s_nop 0
	s_nop 0
	s_nop 0
	s_nop 0
	s_nop 0
	s_nop 0
	s_nop 0
	s_nop 0
	s_nop 0
	s_nop 0
	s_nop 0
	s_nop 0
	s_nop 0
	s_nop 0
	s_nop 0
	s_nop 0
	s_nop 0
	s_nop 0
	s_nop 0
	s_nop 0
	s_nop 0
	s_nop 0
	s_nop 0

; template <class Epi, class Sched, bool ALIGN_EPI = false, bool SP2 = false>
; __device__ __forceinline__ void gemm_phase(PG8_LAS unsigned char* lds, const Gemm g, const Sched& S, const Epi& E, const int wid  ) {
;     ...
;         const bool has_next = S.next(ui + 1, nxt); nxt.same = (has_next && nxt.pm == cur.pm) ? 1 : 0;
;         const unsigned nA = has_next ? (unsigned)g.asel(nxt.pn) * (unsigned)g.a_stride + (unsigned)nxt.pm * tstep : cA, nB = has_next ? (unsigned)nxt.pn * tstep : cB;
;         for (int t = 0; t < nt; t += 2) {
;             const bool last = (t == nt - 2);
;             const unsigned a1 = cA + (unsigned)(t + 1) * kstep;
;             const unsigned a2 = last ? nA : cA + (unsigned)(t + 2) * kstep, b2 = last ? nB : cB + (unsigned)(t + 2) * kstep;
;             const unsigned a3 = a2 + kstep, b3 = b2 + kstep;
;     ...
; #pragma unroll
;         for (int a = 0; a < 2; ++a)
; #pragma unroll
;             for (int b = 0; b < 2; ++b)
; #pragma unroll
;                 for (int m = 0; m < 4; ++m)
; #pragma unroll
;                     for (int n = 0; n < 2; ++n) acc[a][b][m][n] = (f32x4){0.f, 0.f, 0.f, 0.f};
;         cur = nxt; cA = nA; cB = nB; ++ui;
.LBB0_803:
	s_mul_i32 s50, s49, 0x2c0000
	s_and_b64 s[0:1], s[4:5], exec
	s_mul_i32 s51, s48, 0x2c0000
	v_mov_b32_e32 v0, 0
	s_cselect_b32 s0, s50, s54
	s_cselect_b32 s1, s51, s55
	s_add_i32 s54, s54, 0x160080
	s_addk_i32 s55, 0x100
	s_mov_b32 s58, -2
	s_waitcnt lgkmcnt(0)
	v_mov_b32_e32 v1, v0
	v_mov_b32_e32 v2, v0
	v_mov_b32_e32 v3, v0
	v_mov_b32_e32 v4, v0
	v_mov_b32_e32 v5, v0
	v_mov_b32_e32 v6, v0
	v_mov_b32_e32 v7, v0
	v_mov_b32_e32 v16, v0
	v_mov_b32_e32 v17, v0
	v_mov_b32_e32 v18, v0
	v_mov_b32_e32 v19, v0
	v_mov_b32_e32 v20, v0
	v_mov_b32_e32 v21, v0
	v_mov_b32_e32 v22, v0
	v_mov_b32_e32 v23, v0
	v_mov_b32_e32 v32, v0
	v_mov_b32_e32 v33, v0
	v_mov_b32_e32 v34, v0
	v_mov_b32_e32 v35, v0
	v_mov_b32_e32 v36, v0
	v_mov_b32_e32 v37, v0
	v_mov_b32_e32 v38, v0
	v_mov_b32_e32 v39, v0
	v_mov_b32_e32 v48, v0
	v_mov_b32_e32 v49, v0
	v_mov_b32_e32 v50, v0
	v_mov_b32_e32 v51, v0
	v_mov_b32_e32 v52, v0
	v_mov_b32_e32 v53, v0
	v_mov_b32_e32 v54, v0
	v_mov_b32_e32 v55, v0
	v_mov_b32_e32 v8, v0
	v_mov_b32_e32 v9, v0
	v_mov_b32_e32 v10, v0
	v_mov_b32_e32 v11, v0
	v_mov_b32_e32 v12, v0
	v_mov_b32_e32 v13, v0
	v_mov_b32_e32 v14, v0
	v_mov_b32_e32 v15, v0
	v_mov_b32_e32 v24, v0
	v_mov_b32_e32 v25, v0
	v_mov_b32_e32 v26, v0
	v_mov_b32_e32 v27, v0
	v_mov_b32_e32 v28, v0
	v_mov_b32_e32 v29, v0
	v_mov_b32_e32 v30, v0
	v_mov_b32_e32 v31, v0
	v_mov_b32_e32 v40, v0
	v_mov_b32_e32 v41, v0
	v_mov_b32_e32 v42, v0
	v_mov_b32_e32 v43, v0
	v_mov_b32_e32 v44, v0
	v_mov_b32_e32 v45, v0
	v_mov_b32_e32 v46, v0
	v_mov_b32_e32 v47, v0
	v_mov_b32_e32 v56, v0
	v_mov_b32_e32 v57, v0
	v_mov_b32_e32 v58, v0
	v_mov_b32_e32 v59, v0
	v_mov_b32_e32 v60, v0
	v_mov_b32_e32 v61, v0
	v_mov_b32_e32 v62, v0
	v_mov_b32_e32 v63, v0
	v_mov_b32_e32 v64, v0
	v_mov_b32_e32 v65, v0
	v_mov_b32_e32 v66, v0
	v_mov_b32_e32 v67, v0
	v_mov_b32_e32 v68, v0
	v_mov_b32_e32 v69, v0
	v_mov_b32_e32 v70, v0
	v_mov_b32_e32 v71, v0
	v_mov_b32_e32 v80, v0
	v_mov_b32_e32 v81, v0
	v_mov_b32_e32 v82, v0
	v_mov_b32_e32 v83, v0
	v_mov_b32_e32 v84, v0
	v_mov_b32_e32 v85, v0
	v_mov_b32_e32 v86, v0
	v_mov_b32_e32 v87, v0
	v_mov_b32_e32 v96, v0
	v_mov_b32_e32 v97, v0
	v_mov_b32_e32 v98, v0
	v_mov_b32_e32 v99, v0
	v_mov_b32_e32 v100, v0
	v_mov_b32_e32 v101, v0
	v_mov_b32_e32 v102, v0
	v_mov_b32_e32 v103, v0
	v_mov_b32_e32 v112, v0
	v_mov_b32_e32 v113, v0
	v_mov_b32_e32 v114, v0
	v_mov_b32_e32 v115, v0
	v_mov_b32_e32 v116, v0
	v_mov_b32_e32 v117, v0
	v_mov_b32_e32 v118, v0
	v_mov_b32_e32 v119, v0
	v_mov_b32_e32 v72, v0
	v_mov_b32_e32 v73, v0
	v_mov_b32_e32 v74, v0
	v_mov_b32_e32 v75, v0
	v_mov_b32_e32 v76, v0
	v_mov_b32_e32 v77, v0
	v_mov_b32_e32 v78, v0
	v_mov_b32_e32 v79, v0
	v_mov_b32_e32 v88, v0
	v_mov_b32_e32 v89, v0
	v_mov_b32_e32 v90, v0
	v_mov_b32_e32 v91, v0
	v_mov_b32_e32 v92, v0
	v_mov_b32_e32 v93, v0
	v_mov_b32_e32 v94, v0
	v_mov_b32_e32 v95, v0
	v_mov_b32_e32 v104, v0
	v_mov_b32_e32 v105, v0
	v_mov_b32_e32 v106, v0
	v_mov_b32_e32 v107, v0
	v_mov_b32_e32 v108, v0
	v_mov_b32_e32 v109, v0
	v_mov_b32_e32 v110, v0
	v_mov_b32_e32 v111, v0
	v_mov_b32_e32 v120, v0
	v_mov_b32_e32 v121, v0
	v_mov_b32_e32 v122, v0
	v_mov_b32_e32 v123, v0
	v_mov_b32_e32 v124, v0
	v_mov_b32_e32 v125, v0
	v_mov_b32_e32 v126, v0
	v_mov_b32_e32 v127, v0
	s_branch .LBB0_804
	s_nop 0
	s_nop 0
	s_nop 0
	s_nop 0
	s_nop 0
	s_nop 0
	s_nop 0
	s_nop 0
	s_nop 0
	s_nop 0
	s_nop 0
	s_nop 0
	s_nop 0
	s_nop 0
	s_nop 0
	s_nop 0
	s_nop 0
	s_nop 0
	s_nop 0
	s_nop 0
	s_nop 0
	s_nop 0
	s_nop 0
	s_nop 0
	s_nop 0
	s_nop 0
	s_nop 0
	s_nop 0
	s_nop 0
	s_nop 0

; template <class Epi, class Sched, bool ALIGN_EPI = false, bool SP2 = false>
; __device__ __forceinline__ void gemm_phase(PG8_LAS unsigned char* lds, const Gemm g, const Sched& S, const Epi& E, const int wid  ) {
;     ...
;         const bool has_next = S.next(ui + 1, nxt); nxt.same = (has_next && nxt.pm == cur.pm) ? 1 : 0;
;         const unsigned nA = has_next ? (unsigned)g.asel(nxt.pn) * (unsigned)g.a_stride + (unsigned)nxt.pm * tstep : cA, nB = has_next ? (unsigned)nxt.pn * tstep : cB;
;         for (int t = 0; t < nt; t += 2) {
;             const bool last = (t == nt - 2);
;             const unsigned a1 = cA + (unsigned)(t + 1) * kstep;
;             const unsigned a2 = last ? nA : cA + (unsigned)(t + 2) * kstep, b2 = last ? nB : cB + (unsigned)(t + 2) * kstep;
;             const unsigned a3 = a2 + kstep, b3 = b2 + kstep;
;     ...
; #pragma unroll
;         for (int a = 0; a < 2; ++a)
; #pragma unroll
;             for (int b = 0; b < 2; ++b)
; #pragma unroll
;                 for (int m = 0; m < 4; ++m)
; #pragma unroll
;                     for (int n = 0; n < 2; ++n) acc[a][b][m][n] = (f32x4){0.f, 0.f, 0.f, 0.f};
;         cur = nxt; cA = nA; cB = nB; ++ui;
.LBB0_902:
	s_lshl_b32 s70, s69, 20
	s_and_b64 s[14:15], s[4:5], exec
	s_cselect_b32 s33, s70, s41
	s_lshl_b32 s71, s68, 20
	s_and_b64 s[14:15], s[4:5], exec
	v_mov_b32_e32 v0, 0
	s_cselect_b32 s40, s71, s74
	s_add_i32 s41, s41, 0x80080
	s_addk_i32 s74, 0x100
	s_mov_b32 s75, -2
	s_waitcnt lgkmcnt(0)
	v_mov_b32_e32 v1, v0
	v_mov_b32_e32 v2, v0
	v_mov_b32_e32 v3, v0
	v_mov_b32_e32 v4, v0
	v_mov_b32_e32 v5, v0
	s_waitcnt lgkmcnt(6)
	v_mov_b32_e32 v6, v0
	v_mov_b32_e32 v7, v0
	s_waitcnt lgkmcnt(1)
	v_mov_b32_e32 v16, v0
	v_mov_b32_e32 v17, v0
	s_waitcnt lgkmcnt(0)
	v_mov_b32_e32 v18, v0
	v_mov_b32_e32 v19, v0
	v_mov_b32_e32 v20, v0
	v_mov_b32_e32 v21, v0
	v_mov_b32_e32 v22, v0
	v_mov_b32_e32 v23, v0
	v_mov_b32_e32 v32, v0
	v_mov_b32_e32 v33, v0
	v_mov_b32_e32 v34, v0
	v_mov_b32_e32 v35, v0
	v_mov_b32_e32 v36, v0
	v_mov_b32_e32 v37, v0
	v_mov_b32_e32 v38, v0
	v_mov_b32_e32 v39, v0
	v_mov_b32_e32 v48, v0
	v_mov_b32_e32 v49, v0
	v_mov_b32_e32 v50, v0
	v_mov_b32_e32 v51, v0
	v_mov_b32_e32 v52, v0
	v_mov_b32_e32 v53, v0
	v_mov_b32_e32 v54, v0
	v_mov_b32_e32 v55, v0
	v_mov_b32_e32 v8, v0
	v_mov_b32_e32 v9, v0
	v_mov_b32_e32 v10, v0
	v_mov_b32_e32 v11, v0
	v_mov_b32_e32 v12, v0
	v_mov_b32_e32 v13, v0
	v_mov_b32_e32 v14, v0
	v_mov_b32_e32 v15, v0
	v_mov_b32_e32 v24, v0
	v_mov_b32_e32 v25, v0
	v_mov_b32_e32 v26, v0
	v_mov_b32_e32 v27, v0
	v_mov_b32_e32 v28, v0
	v_mov_b32_e32 v29, v0
	v_mov_b32_e32 v30, v0
	v_mov_b32_e32 v31, v0
	v_mov_b32_e32 v40, v0
	v_mov_b32_e32 v41, v0
	v_mov_b32_e32 v42, v0
	v_mov_b32_e32 v43, v0
	v_mov_b32_e32 v44, v0
	v_mov_b32_e32 v45, v0
	v_mov_b32_e32 v46, v0
	v_mov_b32_e32 v47, v0
	v_mov_b32_e32 v56, v0
	v_mov_b32_e32 v57, v0
	v_mov_b32_e32 v58, v0
	v_mov_b32_e32 v59, v0
	v_mov_b32_e32 v60, v0
	v_mov_b32_e32 v61, v0
	v_mov_b32_e32 v62, v0
	v_mov_b32_e32 v63, v0
	v_mov_b32_e32 v64, v0
	v_mov_b32_e32 v65, v0
	v_mov_b32_e32 v66, v0
	v_mov_b32_e32 v67, v0
	v_mov_b32_e32 v68, v0
	v_mov_b32_e32 v69, v0
	v_mov_b32_e32 v70, v0
	v_mov_b32_e32 v71, v0
	v_mov_b32_e32 v80, v0
	v_mov_b32_e32 v81, v0
	v_mov_b32_e32 v82, v0
	v_mov_b32_e32 v83, v0
	v_mov_b32_e32 v84, v0
	v_mov_b32_e32 v85, v0
	v_mov_b32_e32 v86, v0
	v_mov_b32_e32 v87, v0
	v_mov_b32_e32 v96, v0
	v_mov_b32_e32 v97, v0
	v_mov_b32_e32 v98, v0
	v_mov_b32_e32 v99, v0
	v_mov_b32_e32 v100, v0
	v_mov_b32_e32 v101, v0
	v_mov_b32_e32 v102, v0
	v_mov_b32_e32 v103, v0
	v_mov_b32_e32 v112, v0
	v_mov_b32_e32 v113, v0
	v_mov_b32_e32 v114, v0
	v_mov_b32_e32 v115, v0
	v_mov_b32_e32 v116, v0
	v_mov_b32_e32 v117, v0
	v_mov_b32_e32 v118, v0
	v_mov_b32_e32 v119, v0
	v_mov_b32_e32 v72, v0
	v_mov_b32_e32 v73, v0
	v_mov_b32_e32 v74, v0
	v_mov_b32_e32 v75, v0
	v_mov_b32_e32 v76, v0
	v_mov_b32_e32 v77, v0
	v_mov_b32_e32 v78, v0
	v_mov_b32_e32 v79, v0
	v_mov_b32_e32 v88, v0
	v_mov_b32_e32 v89, v0
	v_mov_b32_e32 v90, v0
	v_mov_b32_e32 v91, v0
	v_mov_b32_e32 v92, v0
	v_mov_b32_e32 v93, v0
	v_mov_b32_e32 v94, v0
	v_mov_b32_e32 v95, v0
	v_mov_b32_e32 v104, v0
	v_mov_b32_e32 v105, v0
	v_mov_b32_e32 v106, v0
	v_mov_b32_e32 v107, v0
	v_mov_b32_e32 v108, v0
	v_mov_b32_e32 v109, v0
	v_mov_b32_e32 v110, v0
	v_mov_b32_e32 v111, v0
	v_mov_b32_e32 v120, v0
	v_mov_b32_e32 v121, v0
	v_mov_b32_e32 v122, v0
	v_mov_b32_e32 v123, v0
	v_mov_b32_e32 v124, v0
	v_mov_b32_e32 v125, v0
	v_mov_b32_e32 v126, v0
	v_mov_b32_e32 v127, v0
	s_branch .LBB0_903
	s_nop 0
	s_nop 0
	s_nop 0
	s_nop 0
	s_nop 0
	s_nop 0
	s_nop 0
	s_nop 0
	s_nop 0
	s_nop 0
	s_nop 0
	s_nop 0
	s_nop 0
	s_nop 0
	s_nop 0
	s_nop 0
	s_nop 0
	s_nop 0
	s_nop 0
	s_nop 0
	s_nop 0
	s_nop 0
	s_nop 0
	s_nop 0
	s_nop 0
	s_nop 0
	s_nop 0
	s_nop 0
	s_nop 0
	s_nop 0

; template <class Epi, class Sched, bool ALIGN_EPI = false, bool SP2 = false>
; __device__ __forceinline__ void gemm_phase(PG8_LAS unsigned char* lds, const Gemm g, const Sched& S, const Epi& E, const int wid  ) {
;     ...
;         const bool has_next = S.next(ui + 1, nxt); nxt.same = (has_next && nxt.pm == cur.pm) ? 1 : 0;
;         const unsigned nA = has_next ? (unsigned)g.asel(nxt.pn) * (unsigned)g.a_stride + (unsigned)nxt.pm * tstep : cA, nB = has_next ? (unsigned)nxt.pn * tstep : cB;
;         for (int t = 0; t < nt; t += 2) {
;             const bool last = (t == nt - 2);
;             const unsigned a1 = cA + (unsigned)(t + 1) * kstep;
;             const unsigned a2 = last ? nA : cA + (unsigned)(t + 2) * kstep, b2 = last ? nB : cB + (unsigned)(t + 2) * kstep;
;             const unsigned a3 = a2 + kstep, b3 = b2 + kstep;
;     ...
; #pragma unroll
;         for (int a = 0; a < 2; ++a)
; #pragma unroll
;             for (int b = 0; b < 2; ++b)
; #pragma unroll
;                 for (int m = 0; m < 4; ++m)
; #pragma unroll
;                     for (int n = 0; n < 2; ++n) acc[a][b][m][n] = (f32x4){0.f, 0.f, 0.f, 0.f};
;         cur = nxt; cA = nA; cB = nB; ++ui;
.LBB0_1075:
	s_lshl_b32 s58, s51, 20
	s_and_b64 s[0:1], s[0:1], exec
	v_mov_b32_e32 v0, 0
	s_cselect_b32 s0, s58, s16
	s_add_i32 s1, s20, 0x80080
	s_addk_i32 s16, 0x100
	s_mov_b32 s20, -2
	v_mov_b32_e32 v1, v0
	v_mov_b32_e32 v2, v0
	v_mov_b32_e32 v3, v0
	v_mov_b32_e32 v4, v0
	v_mov_b32_e32 v5, v0
	v_mov_b32_e32 v6, v0
	v_mov_b32_e32 v7, v0
	v_mov_b32_e32 v16, v0
	v_mov_b32_e32 v17, v0
	v_mov_b32_e32 v18, v0
	v_mov_b32_e32 v19, v0
	v_mov_b32_e32 v20, v0
	v_mov_b32_e32 v21, v0
	v_mov_b32_e32 v22, v0
	v_mov_b32_e32 v23, v0
	v_mov_b32_e32 v32, v0
	v_mov_b32_e32 v33, v0
	v_mov_b32_e32 v34, v0
	v_mov_b32_e32 v35, v0
	v_mov_b32_e32 v36, v0
	v_mov_b32_e32 v37, v0
	v_mov_b32_e32 v38, v0
	v_mov_b32_e32 v39, v0
	v_mov_b32_e32 v48, v0
	v_mov_b32_e32 v49, v0
	v_mov_b32_e32 v50, v0
	v_mov_b32_e32 v51, v0
	v_mov_b32_e32 v52, v0
	v_mov_b32_e32 v53, v0
	v_mov_b32_e32 v54, v0
	v_mov_b32_e32 v55, v0
	v_mov_b32_e32 v8, v0
	v_mov_b32_e32 v9, v0
	v_mov_b32_e32 v10, v0
	v_mov_b32_e32 v11, v0
	v_mov_b32_e32 v12, v0
	v_mov_b32_e32 v13, v0
	v_mov_b32_e32 v14, v0
	v_mov_b32_e32 v15, v0
	v_mov_b32_e32 v24, v0
	v_mov_b32_e32 v25, v0
	v_mov_b32_e32 v26, v0
	v_mov_b32_e32 v27, v0
	v_mov_b32_e32 v28, v0
	v_mov_b32_e32 v29, v0
	v_mov_b32_e32 v30, v0
	v_mov_b32_e32 v31, v0
	v_mov_b32_e32 v40, v0
	v_mov_b32_e32 v41, v0
	v_mov_b32_e32 v42, v0
	v_mov_b32_e32 v43, v0
	v_mov_b32_e32 v44, v0
	v_mov_b32_e32 v45, v0
	v_mov_b32_e32 v46, v0
	v_mov_b32_e32 v47, v0
	v_mov_b32_e32 v56, v0
	v_mov_b32_e32 v57, v0
	v_mov_b32_e32 v58, v0
	v_mov_b32_e32 v59, v0
	v_mov_b32_e32 v60, v0
	v_mov_b32_e32 v61, v0
	v_mov_b32_e32 v62, v0
	v_mov_b32_e32 v63, v0
	v_mov_b32_e32 v64, v0
	v_mov_b32_e32 v65, v0
	v_mov_b32_e32 v66, v0
	v_mov_b32_e32 v67, v0
	v_mov_b32_e32 v68, v0
	v_mov_b32_e32 v69, v0
	v_mov_b32_e32 v70, v0
	v_mov_b32_e32 v71, v0
	v_mov_b32_e32 v80, v0
	v_mov_b32_e32 v81, v0
	v_mov_b32_e32 v82, v0
	v_mov_b32_e32 v83, v0
	v_mov_b32_e32 v84, v0
	v_mov_b32_e32 v85, v0
	v_mov_b32_e32 v86, v0
	v_mov_b32_e32 v87, v0
	v_mov_b32_e32 v96, v0
	v_mov_b32_e32 v97, v0
	v_mov_b32_e32 v98, v0
	v_mov_b32_e32 v99, v0
	v_mov_b32_e32 v100, v0
	v_mov_b32_e32 v101, v0
	v_mov_b32_e32 v102, v0
	v_mov_b32_e32 v103, v0
	v_mov_b32_e32 v112, v0
	v_mov_b32_e32 v113, v0
	v_mov_b32_e32 v114, v0
	v_mov_b32_e32 v115, v0
	v_mov_b32_e32 v116, v0
	v_mov_b32_e32 v117, v0
	v_mov_b32_e32 v118, v0
	v_mov_b32_e32 v119, v0
	v_mov_b32_e32 v72, v0
	v_mov_b32_e32 v73, v0
	v_mov_b32_e32 v74, v0
	v_mov_b32_e32 v75, v0
	v_mov_b32_e32 v76, v0
	v_mov_b32_e32 v77, v0
	v_mov_b32_e32 v78, v0
	v_mov_b32_e32 v79, v0
	v_mov_b32_e32 v88, v0
	v_mov_b32_e32 v89, v0
	v_mov_b32_e32 v90, v0
	v_mov_b32_e32 v91, v0
	v_mov_b32_e32 v92, v0
	v_mov_b32_e32 v93, v0
	v_mov_b32_e32 v94, v0
	v_mov_b32_e32 v95, v0
	v_mov_b32_e32 v104, v0
	v_mov_b32_e32 v105, v0
	v_mov_b32_e32 v106, v0
	v_mov_b32_e32 v107, v0
	v_mov_b32_e32 v108, v0
	v_mov_b32_e32 v109, v0
	v_mov_b32_e32 v110, v0
	v_mov_b32_e32 v111, v0
	v_mov_b32_e32 v120, v0
	v_mov_b32_e32 v121, v0
	v_mov_b32_e32 v122, v0
	v_mov_b32_e32 v123, v0
	v_mov_b32_e32 v124, v0
	v_mov_b32_e32 v125, v0
	v_mov_b32_e32 v126, v0
	v_mov_b32_e32 v127, v0
	s_branch .LBB0_1076
	s_nop 0
	s_nop 0
	s_nop 0
	s_nop 0
	s_nop 0
	s_nop 0
	s_nop 0
	s_nop 0
	s_nop 0
	s_nop 0
	s_nop 0
	s_nop 0
	s_nop 0
	s_nop 0
	s_nop 0
	s_nop 0
	s_nop 0
	s_nop 0
	s_nop 0
	s_nop 0
	s_nop 0
	s_nop 0
	s_nop 0
	s_nop 0
	s_nop 0
	s_nop 0
	s_nop 0
	s_nop 0
	s_nop 0
	s_nop 0

; template <class Epi, class Sched, bool ALIGN_EPI = false, bool SP2 = false>
; __device__ __forceinline__ void gemm_phase(PG8_LAS unsigned char* lds, const Gemm g, const Sched& S, const Epi& E, const int wid  ) {
;     ...
;         const bool has_next = S.next(ui + 1, nxt); nxt.same = (has_next && nxt.pm == cur.pm) ? 1 : 0;
;         const unsigned nA = has_next ? (unsigned)g.asel(nxt.pn) * (unsigned)g.a_stride + (unsigned)nxt.pm * tstep : cA, nB = has_next ? (unsigned)nxt.pn * tstep : cB;
;         for (int t = 0; t < nt; t += 2) {
;             const bool last = (t == nt - 2);
;             const unsigned a1 = cA + (unsigned)(t + 1) * kstep;
;             const unsigned a2 = last ? nA : cA + (unsigned)(t + 2) * kstep, b2 = last ? nB : cB + (unsigned)(t + 2) * kstep;
;             const unsigned a3 = a2 + kstep, b3 = b2 + kstep;
;     ...
; #pragma unroll
;         for (int a = 0; a < 2; ++a)
; #pragma unroll
;             for (int b = 0; b < 2; ++b)
; #pragma unroll
;                 for (int m = 0; m < 4; ++m)
; #pragma unroll
;                     for (int n = 0; n < 2; ++n) acc[a][b][m][n] = (f32x4){0.f, 0.f, 0.f, 0.f};
;         cur = nxt; cA = nA; cB = nB; ++ui;
.LBB0_1942:
	s_lshl_b32 s50, s49, 20
	s_and_b64 s[0:1], s[4:5], exec
	s_cselect_b32 s0, s50, s54
	s_lshl_b32 s51, s48, 20
	s_and_b64 s[14:15], s[4:5], exec
	v_mov_b32_e32 v0, 0
	s_cselect_b32 s1, s51, s55
	s_add_i32 s54, s54, 0x80080
	s_addk_i32 s55, 0x100
	s_mov_b32 s58, -2
	s_waitcnt lgkmcnt(0)
	v_mov_b32_e32 v1, v0
	v_mov_b32_e32 v2, v0
	v_mov_b32_e32 v3, v0
	v_mov_b32_e32 v4, v0
	v_mov_b32_e32 v5, v0
	v_mov_b32_e32 v6, v0
	v_mov_b32_e32 v7, v0
	v_mov_b32_e32 v16, v0
	v_mov_b32_e32 v17, v0
	v_mov_b32_e32 v18, v0
	v_mov_b32_e32 v19, v0
	s_waitcnt vmcnt(21)
	v_mov_b32_e32 v20, v0
	v_mov_b32_e32 v21, v0
	v_mov_b32_e32 v22, v0
	v_mov_b32_e32 v23, v0
	v_mov_b32_e32 v32, v0
	v_mov_b32_e32 v33, v0
	v_mov_b32_e32 v34, v0
	v_mov_b32_e32 v35, v0
	v_mov_b32_e32 v36, v0
	v_mov_b32_e32 v37, v0
	v_mov_b32_e32 v38, v0
	v_mov_b32_e32 v39, v0
	v_mov_b32_e32 v48, v0
	v_mov_b32_e32 v49, v0
	s_waitcnt vmcnt(16)
	v_mov_b32_e32 v50, v0
	v_mov_b32_e32 v51, v0
	v_mov_b32_e32 v52, v0
	v_mov_b32_e32 v53, v0
	v_mov_b32_e32 v54, v0
	v_mov_b32_e32 v55, v0
	v_mov_b32_e32 v8, v0
	v_mov_b32_e32 v9, v0
	v_mov_b32_e32 v10, v0
	v_mov_b32_e32 v11, v0
	v_mov_b32_e32 v12, v0
	v_mov_b32_e32 v13, v0
	v_mov_b32_e32 v14, v0
	v_mov_b32_e32 v15, v0
	v_mov_b32_e32 v24, v0
	v_mov_b32_e32 v25, v0
	v_mov_b32_e32 v26, v0
	v_mov_b32_e32 v27, v0
	v_mov_b32_e32 v28, v0
	v_mov_b32_e32 v29, v0
	v_mov_b32_e32 v30, v0
	v_mov_b32_e32 v31, v0
	v_mov_b32_e32 v40, v0
	v_mov_b32_e32 v41, v0
	v_mov_b32_e32 v42, v0
	v_mov_b32_e32 v43, v0
	v_mov_b32_e32 v44, v0
	v_mov_b32_e32 v45, v0
	v_mov_b32_e32 v46, v0
	v_mov_b32_e32 v47, v0
	v_mov_b32_e32 v56, v0
	v_mov_b32_e32 v57, v0
	v_mov_b32_e32 v58, v0
	v_mov_b32_e32 v59, v0
	v_mov_b32_e32 v60, v0
	v_mov_b32_e32 v61, v0
	v_mov_b32_e32 v62, v0
	v_mov_b32_e32 v63, v0
	v_mov_b32_e32 v64, v0
	v_mov_b32_e32 v65, v0
	s_waitcnt vmcnt(15)
	v_mov_b32_e32 v66, v0
	v_mov_b32_e32 v67, v0
	v_mov_b32_e32 v68, v0
	v_mov_b32_e32 v69, v0
	v_mov_b32_e32 v70, v0
	v_mov_b32_e32 v71, v0
	v_mov_b32_e32 v80, v0
	v_mov_b32_e32 v81, v0
	v_mov_b32_e32 v82, v0
	v_mov_b32_e32 v83, v0
	v_mov_b32_e32 v84, v0
	v_mov_b32_e32 v85, v0
	v_mov_b32_e32 v86, v0
	v_mov_b32_e32 v87, v0
	v_mov_b32_e32 v96, v0
	v_mov_b32_e32 v97, v0
	v_mov_b32_e32 v98, v0
	v_mov_b32_e32 v99, v0
	v_mov_b32_e32 v100, v0
	v_mov_b32_e32 v101, v0
	v_mov_b32_e32 v102, v0
	v_mov_b32_e32 v103, v0
	v_mov_b32_e32 v112, v0
	v_mov_b32_e32 v113, v0
	v_mov_b32_e32 v114, v0
	v_mov_b32_e32 v115, v0
	v_mov_b32_e32 v116, v0
	v_mov_b32_e32 v117, v0
	v_mov_b32_e32 v118, v0
	v_mov_b32_e32 v119, v0
	v_mov_b32_e32 v72, v0
	v_mov_b32_e32 v73, v0
	v_mov_b32_e32 v74, v0
	v_mov_b32_e32 v75, v0
	v_mov_b32_e32 v76, v0
	v_mov_b32_e32 v77, v0
	v_mov_b32_e32 v78, v0
	v_mov_b32_e32 v79, v0
	v_mov_b32_e32 v88, v0
	v_mov_b32_e32 v89, v0
	v_mov_b32_e32 v90, v0
	v_mov_b32_e32 v91, v0
	v_mov_b32_e32 v92, v0
	v_mov_b32_e32 v93, v0
	v_mov_b32_e32 v94, v0
	v_mov_b32_e32 v95, v0
	v_mov_b32_e32 v104, v0
	v_mov_b32_e32 v105, v0
	v_mov_b32_e32 v106, v0
	v_mov_b32_e32 v107, v0
	v_mov_b32_e32 v108, v0
	v_mov_b32_e32 v109, v0
	v_mov_b32_e32 v110, v0
	v_mov_b32_e32 v111, v0
	v_mov_b32_e32 v120, v0
	v_mov_b32_e32 v121, v0
	v_mov_b32_e32 v122, v0
	v_mov_b32_e32 v123, v0
	v_mov_b32_e32 v124, v0
	v_mov_b32_e32 v125, v0
	v_mov_b32_e32 v126, v0
	v_mov_b32_e32 v127, v0
	s_branch .LBB0_1943
	s_nop 0
	s_nop 0
	s_nop 0
	s_nop 0
	s_nop 0
	s_nop 0
	s_nop 0
	s_nop 0
	s_nop 0
	s_nop 0
	s_nop 0
	s_nop 0
	s_nop 0
	s_nop 0
	s_nop 0
	s_nop 0
	s_nop 0
	s_nop 0
	s_nop 0
	s_nop 0
	s_nop 0
	s_nop 0
	s_nop 0
	s_nop 0
	s_nop 0
	s_nop 0
	s_nop 0
	s_nop 0
	s_nop 0
	s_nop 0

; template <class Epi, class Sched, bool ALIGN_EPI = false, bool SP2 = false>
; __device__ __forceinline__ void gemm_phase(PG8_LAS unsigned char* lds, const Gemm g, const Sched& S, const Epi& E, const int wid  ) {
;     ...
;         const bool has_next = S.next(ui + 1, nxt); nxt.same = (has_next && nxt.pm == cur.pm) ? 1 : 0;
;         const unsigned nA = has_next ? (unsigned)g.asel(nxt.pn) * (unsigned)g.a_stride + (unsigned)nxt.pm * tstep : cA, nB = has_next ? (unsigned)nxt.pn * tstep : cB;
;         for (int t = 0; t < nt; t += 2) {
;             const bool last = (t == nt - 2);
;             const unsigned a1 = cA + (unsigned)(t + 1) * kstep;
;             const unsigned a2 = last ? nA : cA + (unsigned)(t + 2) * kstep, b2 = last ? nB : cB + (unsigned)(t + 2) * kstep;
;             const unsigned a3 = a2 + kstep, b3 = b2 + kstep;
;     ...
; #pragma unroll
;         for (int a = 0; a < 2; ++a)
; #pragma unroll
;             for (int b = 0; b < 2; ++b)
; #pragma unroll
;                 for (int m = 0; m < 4; ++m)
; #pragma unroll
;                     for (int n = 0; n < 2; ++n) acc[a][b][m][n] = (f32x4){0.f, 0.f, 0.f, 0.f};
;         cur = nxt; cA = nA; cB = nB; ++ui;
.LBB0_2036:
	s_lshl_b32 s90, s89, 20
	s_and_b64 s[6:7], s[4:5], exec
	s_cselect_b32 s6, s90, s48
	s_lshl_b32 s91, s88, 20
	s_and_b64 s[18:19], s[4:5], exec
	v_mov_b32_e32 v56, 0
	s_cselect_b32 s7, s91, s9
	s_add_i32 s8, s48, 0x80080
	s_addk_i32 s9, 0x100
	s_mov_b32 s48, -2
	v_mov_b32_e32 v57, v56
	v_mov_b32_e32 v58, v56
	v_mov_b32_e32 v59, v56
	v_mov_b32_e32 v60, v56
	v_mov_b32_e32 v61, v56
	v_mov_b32_e32 v62, v56
	v_mov_b32_e32 v63, v56
	v_mov_b32_e32 v64, v56
	v_mov_b32_e32 v65, v56
	v_mov_b32_e32 v66, v56
	v_mov_b32_e32 v67, v56
	v_mov_b32_e32 v68, v56
	v_mov_b32_e32 v69, v56
	v_mov_b32_e32 v70, v56
	v_mov_b32_e32 v71, v56
	v_mov_b32_e32 v72, v56
	v_mov_b32_e32 v73, v56
	v_mov_b32_e32 v74, v56
	v_mov_b32_e32 v75, v56
	v_mov_b32_e32 v80, v56
	v_mov_b32_e32 v81, v56
	v_mov_b32_e32 v82, v56
	v_mov_b32_e32 v83, v56
	v_mov_b32_e32 v0, v56
	v_mov_b32_e32 v1, v56
	s_waitcnt lgkmcnt(7)
	v_mov_b32_e32 v2, v56
	v_mov_b32_e32 v3, v56
	s_waitcnt lgkmcnt(6)
	v_mov_b32_e32 v4, v56
	v_mov_b32_e32 v5, v56
	s_waitcnt lgkmcnt(5)
	v_mov_b32_e32 v6, v56
	v_mov_b32_e32 v7, v56
	v_mov_b32_e32 v48, v56
	v_mov_b32_e32 v49, v56
	v_mov_b32_e32 v50, v56
	v_mov_b32_e32 v51, v56
	v_mov_b32_e32 v92, v56
	v_mov_b32_e32 v93, v56
	v_mov_b32_e32 v94, v56
	v_mov_b32_e32 v95, v56
	v_mov_b32_e32 v76, v56
	v_mov_b32_e32 v77, v56
	v_mov_b32_e32 v78, v56
	v_mov_b32_e32 v79, v56
	v_mov_b32_e32 v84, v56
	v_mov_b32_e32 v85, v56
	v_mov_b32_e32 v86, v56
	v_mov_b32_e32 v87, v56
	v_mov_b32_e32 v88, v56
	v_mov_b32_e32 v89, v56
	v_mov_b32_e32 v90, v56
	v_mov_b32_e32 v91, v56
	v_mov_b32_e32 v96, v56
	v_mov_b32_e32 v97, v56
	v_mov_b32_e32 v98, v56
	v_mov_b32_e32 v99, v56
	v_mov_b32_e32 v100, v56
	v_mov_b32_e32 v101, v56
	v_mov_b32_e32 v102, v56
	v_mov_b32_e32 v103, v56
	v_mov_b32_e32 v104, v56
	v_mov_b32_e32 v105, v56
	v_mov_b32_e32 v106, v56
	v_mov_b32_e32 v107, v56
	v_mov_b32_e32 v108, v56
	v_mov_b32_e32 v109, v56
	v_mov_b32_e32 v110, v56
	v_mov_b32_e32 v111, v56
	v_mov_b32_e32 v112, v56
	v_mov_b32_e32 v113, v56
	v_mov_b32_e32 v114, v56
	v_mov_b32_e32 v115, v56
	v_mov_b32_e32 v116, v56
	v_mov_b32_e32 v117, v56
	v_mov_b32_e32 v118, v56
	v_mov_b32_e32 v119, v56
	v_mov_b32_e32 v124, v56
	v_mov_b32_e32 v125, v56
	v_mov_b32_e32 v126, v56
	v_mov_b32_e32 v127, v56
	v_mov_b32_e32 v128, v56
	v_mov_b32_e32 v129, v56
	v_mov_b32_e32 v130, v56
	v_mov_b32_e32 v131, v56
	v_mov_b32_e32 v136, v56
	v_mov_b32_e32 v137, v56
	v_mov_b32_e32 v138, v56
	v_mov_b32_e32 v139, v56
	s_waitcnt lgkmcnt(4)
	v_mov_b32_e32 v8, v56
	v_mov_b32_e32 v9, v56
	s_waitcnt lgkmcnt(3)
	v_mov_b32_e32 v10, v56
	v_mov_b32_e32 v11, v56
	s_waitcnt lgkmcnt(2)
	v_mov_b32_e32 v12, v56
	v_mov_b32_e32 v13, v56
	s_waitcnt lgkmcnt(1)
	v_mov_b32_e32 v14, v56
	v_mov_b32_e32 v15, v56
	v_mov_b32_e32 v120, v56
	v_mov_b32_e32 v121, v56
	v_mov_b32_e32 v122, v56
	v_mov_b32_e32 v123, v56
	v_mov_b32_e32 v156, v56
	v_mov_b32_e32 v157, v56
	v_mov_b32_e32 v158, v56
	v_mov_b32_e32 v159, v56
	v_mov_b32_e32 v132, v56
	v_mov_b32_e32 v133, v56
	v_mov_b32_e32 v134, v56
	v_mov_b32_e32 v135, v56
	v_mov_b32_e32 v140, v56
	v_mov_b32_e32 v141, v56
	v_mov_b32_e32 v142, v56
	v_mov_b32_e32 v143, v56
	v_mov_b32_e32 v144, v56
	v_mov_b32_e32 v145, v56
	v_mov_b32_e32 v146, v56
	v_mov_b32_e32 v147, v56
	v_mov_b32_e32 v148, v56
	v_mov_b32_e32 v149, v56
	v_mov_b32_e32 v150, v56
	v_mov_b32_e32 v151, v56
	v_mov_b32_e32 v52, v56
	v_mov_b32_e32 v53, v56
	v_mov_b32_e32 v54, v56
	v_mov_b32_e32 v55, v56
	v_mov_b32_e32 v152, v56
	v_mov_b32_e32 v153, v56
	v_mov_b32_e32 v154, v56
	v_mov_b32_e32 v155, v56
	s_branch .LBB0_2037
	s_nop 0
	s_nop 0
	s_nop 0
	s_nop 0
	s_nop 0
	s_nop 0
	s_nop 0
	s_nop 0
	s_nop 0
	s_nop 0
	s_nop 0
	s_nop 0
	s_nop 0
	s_nop 0
	s_nop 0
	s_nop 0
	s_nop 0
	s_nop 0
	s_nop 0
	s_nop 0
	s_nop 0
	s_nop 0
	s_nop 0
	s_nop 0
	s_nop 0
	s_nop 0
	s_nop 0
	s_nop 0
	s_nop 0
	s_nop 0

; template <class Epi, class Sched, bool ALIGN_EPI = false, bool SP2 = false>
; __device__ __forceinline__ void gemm_phase(PG8_LAS unsigned char* lds, const Gemm g, const Sched& S, const Epi& E, const int wid  ) {
;     ...
;         const bool has_next = S.next(ui + 1, nxt); nxt.same = (has_next && nxt.pm == cur.pm) ? 1 : 0;
;         const unsigned nA = has_next ? (unsigned)g.asel(nxt.pn) * (unsigned)g.a_stride + (unsigned)nxt.pm * tstep : cA, nB = has_next ? (unsigned)nxt.pn * tstep : cB;
;         for (int t = 0; t < nt; t += 2) {
;             const bool last = (t == nt - 2);
;             const unsigned a1 = cA + (unsigned)(t + 1) * kstep;
;             const unsigned a2 = last ? nA : cA + (unsigned)(t + 2) * kstep, b2 = last ? nB : cB + (unsigned)(t + 2) * kstep;
;             const unsigned a3 = a2 + kstep, b3 = b2 + kstep;
;     ...
; #pragma unroll
;         for (int a = 0; a < 2; ++a)
; #pragma unroll
;             for (int b = 0; b < 2; ++b)
; #pragma unroll
;                 for (int m = 0; m < 4; ++m)
; #pragma unroll
;                     for (int n = 0; n < 2; ++n) acc[a][b][m][n] = (f32x4){0.f, 0.f, 0.f, 0.f};
;         cur = nxt; cA = nA; cB = nB; ++ui;
.LBB0_2379:
	s_mul_i32 s50, s49, 0x2c0000
	s_and_b64 s[0:1], s[4:5], exec
	s_mul_i32 s51, s48, 0x2c0000
	v_mov_b32_e32 v0, 0
	s_cselect_b32 s0, s50, s16
	s_cselect_b32 s1, s51, s55
	s_add_i32 s16, s16, 0x160080
	s_addk_i32 s55, 0x100
	s_mov_b32 s58, -2
	s_waitcnt lgkmcnt(0)
	v_mov_b32_e32 v1, v0
	v_mov_b32_e32 v2, v0
	v_mov_b32_e32 v3, v0
	v_mov_b32_e32 v4, v0
	v_mov_b32_e32 v5, v0
	v_mov_b32_e32 v6, v0
	v_mov_b32_e32 v7, v0
	v_mov_b32_e32 v16, v0
	v_mov_b32_e32 v17, v0
	v_mov_b32_e32 v18, v0
	v_mov_b32_e32 v19, v0
	v_mov_b32_e32 v20, v0
	v_mov_b32_e32 v21, v0
	v_mov_b32_e32 v22, v0
	v_mov_b32_e32 v23, v0
	v_mov_b32_e32 v32, v0
	v_mov_b32_e32 v33, v0
	v_mov_b32_e32 v34, v0
	v_mov_b32_e32 v35, v0
	v_mov_b32_e32 v36, v0
	v_mov_b32_e32 v37, v0
	v_mov_b32_e32 v38, v0
	v_mov_b32_e32 v39, v0
	v_mov_b32_e32 v48, v0
	v_mov_b32_e32 v49, v0
	v_mov_b32_e32 v50, v0
	v_mov_b32_e32 v51, v0
	v_mov_b32_e32 v52, v0
	v_mov_b32_e32 v53, v0
	v_mov_b32_e32 v54, v0
	v_mov_b32_e32 v55, v0
	v_mov_b32_e32 v8, v0
	v_mov_b32_e32 v9, v0
	v_mov_b32_e32 v10, v0
	v_mov_b32_e32 v11, v0
	v_mov_b32_e32 v12, v0
	v_mov_b32_e32 v13, v0
	v_mov_b32_e32 v14, v0
	v_mov_b32_e32 v15, v0
	v_mov_b32_e32 v24, v0
	v_mov_b32_e32 v25, v0
	v_mov_b32_e32 v26, v0
	v_mov_b32_e32 v27, v0
	v_mov_b32_e32 v28, v0
	v_mov_b32_e32 v29, v0
	v_mov_b32_e32 v30, v0
	v_mov_b32_e32 v31, v0
	v_mov_b32_e32 v40, v0
	v_mov_b32_e32 v41, v0
	v_mov_b32_e32 v42, v0
	v_mov_b32_e32 v43, v0
	v_mov_b32_e32 v44, v0
	v_mov_b32_e32 v45, v0
	v_mov_b32_e32 v46, v0
	v_mov_b32_e32 v47, v0
	v_mov_b32_e32 v56, v0
	v_mov_b32_e32 v57, v0
	v_mov_b32_e32 v58, v0
	v_mov_b32_e32 v59, v0
	v_mov_b32_e32 v60, v0
	v_mov_b32_e32 v61, v0
	v_mov_b32_e32 v62, v0
	v_mov_b32_e32 v63, v0
	v_mov_b32_e32 v64, v0
	v_mov_b32_e32 v65, v0
	s_waitcnt vmcnt(15)
	v_mov_b32_e32 v66, v0
	v_mov_b32_e32 v67, v0
	v_mov_b32_e32 v68, v0
	v_mov_b32_e32 v69, v0
	v_mov_b32_e32 v70, v0
	v_mov_b32_e32 v71, v0
	v_mov_b32_e32 v80, v0
	v_mov_b32_e32 v81, v0
	v_mov_b32_e32 v82, v0
	v_mov_b32_e32 v83, v0
	v_mov_b32_e32 v84, v0
	v_mov_b32_e32 v85, v0
	v_mov_b32_e32 v86, v0
	v_mov_b32_e32 v87, v0
	v_mov_b32_e32 v96, v0
	v_mov_b32_e32 v97, v0
	v_mov_b32_e32 v98, v0
	v_mov_b32_e32 v99, v0
	v_mov_b32_e32 v100, v0
	v_mov_b32_e32 v101, v0
	v_mov_b32_e32 v102, v0
	v_mov_b32_e32 v103, v0
	v_mov_b32_e32 v112, v0
	v_mov_b32_e32 v113, v0
	v_mov_b32_e32 v114, v0
	v_mov_b32_e32 v115, v0
	v_mov_b32_e32 v116, v0
	v_mov_b32_e32 v117, v0
	v_mov_b32_e32 v118, v0
	v_mov_b32_e32 v119, v0
	v_mov_b32_e32 v72, v0
	v_mov_b32_e32 v73, v0
	v_mov_b32_e32 v74, v0
	v_mov_b32_e32 v75, v0
	v_mov_b32_e32 v76, v0
	v_mov_b32_e32 v77, v0
	v_mov_b32_e32 v78, v0
	v_mov_b32_e32 v79, v0
	v_mov_b32_e32 v88, v0
	v_mov_b32_e32 v89, v0
	v_mov_b32_e32 v90, v0
	v_mov_b32_e32 v91, v0
	v_mov_b32_e32 v92, v0
	v_mov_b32_e32 v93, v0
	v_mov_b32_e32 v94, v0
	v_mov_b32_e32 v95, v0
	v_mov_b32_e32 v104, v0
	v_mov_b32_e32 v105, v0
	v_mov_b32_e32 v106, v0
	v_mov_b32_e32 v107, v0
	v_mov_b32_e32 v108, v0
	v_mov_b32_e32 v109, v0
	v_mov_b32_e32 v110, v0
	v_mov_b32_e32 v111, v0
	v_mov_b32_e32 v120, v0
	v_mov_b32_e32 v121, v0
	v_mov_b32_e32 v122, v0
	v_mov_b32_e32 v123, v0
	v_mov_b32_e32 v124, v0
	v_mov_b32_e32 v125, v0
	v_mov_b32_e32 v126, v0
	v_mov_b32_e32 v127, v0
	s_branch .LBB0_2380
	s_nop 0
	s_nop 0
	s_nop 0
	s_nop 0
	s_nop 0
	s_nop 0
	s_nop 0
	s_nop 0
	s_nop 0
	s_nop 0
	s_nop 0
	s_nop 0
	s_nop 0
	s_nop 0
	s_nop 0
	s_nop 0
	s_nop 0
	s_nop 0
	s_nop 0
	s_nop 0
	s_nop 0
	s_nop 0
	s_nop 0
	s_nop 0
	s_nop 0
	s_nop 0
	s_nop 0
	s_nop 0
	s_nop 0
	s_nop 0

; template <class Epi, class Sched, bool ALIGN_EPI = false, bool SP2 = false>
; __device__ __forceinline__ void gemm_phase(PG8_LAS unsigned char* lds, const Gemm g, const Sched& S, const Epi& E, const int wid  ) {
;     ...
;         const bool has_next = S.next(ui + 1, nxt); nxt.same = (has_next && nxt.pm == cur.pm) ? 1 : 0;
;         const unsigned nA = has_next ? (unsigned)g.asel(nxt.pn) * (unsigned)g.a_stride + (unsigned)nxt.pm * tstep : cA, nB = has_next ? (unsigned)nxt.pn * tstep : cB;
;         for (int t = 0; t < nt; t += 2) {
;             const bool last = (t == nt - 2);
;             const unsigned a1 = cA + (unsigned)(t + 1) * kstep;
;             const unsigned a2 = last ? nA : cA + (unsigned)(t + 2) * kstep, b2 = last ? nB : cB + (unsigned)(t + 2) * kstep;
;             const unsigned a3 = a2 + kstep, b3 = b2 + kstep;
;     ...
; #pragma unroll
;         for (int a = 0; a < 2; ++a)
; #pragma unroll
;             for (int b = 0; b < 2; ++b)
; #pragma unroll
;                 for (int m = 0; m < 4; ++m)
; #pragma unroll
;                     for (int n = 0; n < 2; ++n) acc[a][b][m][n] = (f32x4){0.f, 0.f, 0.f, 0.f};
;         cur = nxt; cA = nA; cB = nB; ++ui;
.LBB0_4015:
	s_lshl_b32 s70, s69, 20
	s_and_b64 s[14:15], s[4:5], exec
	s_cselect_b32 s33, s70, s41
	s_lshl_b32 s71, s68, 20
	s_and_b64 s[14:15], s[4:5], exec
	v_mov_b32_e32 v0, 0
	s_cselect_b32 s40, s71, s73
	s_add_i32 s41, s41, 0x80080
	s_add_i32 s72, s73, 0x100
	s_mov_b32 s73, -2
	s_waitcnt lgkmcnt(0)
	v_mov_b32_e32 v1, v0
	v_mov_b32_e32 v2, v0
	v_mov_b32_e32 v3, v0
	v_mov_b32_e32 v4, v0
	v_mov_b32_e32 v5, v0
	s_waitcnt lgkmcnt(6)
	v_mov_b32_e32 v6, v0
	v_mov_b32_e32 v7, v0
	s_waitcnt lgkmcnt(1)
	v_mov_b32_e32 v16, v0
	v_mov_b32_e32 v17, v0
	s_waitcnt lgkmcnt(0)
	v_mov_b32_e32 v18, v0
	v_mov_b32_e32 v19, v0
	v_mov_b32_e32 v20, v0
	v_mov_b32_e32 v21, v0
	v_mov_b32_e32 v22, v0
	v_mov_b32_e32 v23, v0
	v_mov_b32_e32 v32, v0
	v_mov_b32_e32 v33, v0
	v_mov_b32_e32 v34, v0
	v_mov_b32_e32 v35, v0
	v_mov_b32_e32 v36, v0
	v_mov_b32_e32 v37, v0
	v_mov_b32_e32 v38, v0
	v_mov_b32_e32 v39, v0
	v_mov_b32_e32 v48, v0
	v_mov_b32_e32 v49, v0
	v_mov_b32_e32 v50, v0
	v_mov_b32_e32 v51, v0
	v_mov_b32_e32 v52, v0
	v_mov_b32_e32 v53, v0
	v_mov_b32_e32 v54, v0
	v_mov_b32_e32 v55, v0
	v_mov_b32_e32 v8, v0
	v_mov_b32_e32 v9, v0
	v_mov_b32_e32 v10, v0
	v_mov_b32_e32 v11, v0
	v_mov_b32_e32 v12, v0
	v_mov_b32_e32 v13, v0
	v_mov_b32_e32 v14, v0
	v_mov_b32_e32 v15, v0
	v_mov_b32_e32 v24, v0
	v_mov_b32_e32 v25, v0
	v_mov_b32_e32 v26, v0
	v_mov_b32_e32 v27, v0
	v_mov_b32_e32 v28, v0
	v_mov_b32_e32 v29, v0
	v_mov_b32_e32 v30, v0
	v_mov_b32_e32 v31, v0
	v_mov_b32_e32 v40, v0
	v_mov_b32_e32 v41, v0
	v_mov_b32_e32 v42, v0
	v_mov_b32_e32 v43, v0
	v_mov_b32_e32 v44, v0
	v_mov_b32_e32 v45, v0
	v_mov_b32_e32 v46, v0
	v_mov_b32_e32 v47, v0
	v_mov_b32_e32 v56, v0
	v_mov_b32_e32 v57, v0
	v_mov_b32_e32 v58, v0
	v_mov_b32_e32 v59, v0
	v_mov_b32_e32 v60, v0
	v_mov_b32_e32 v61, v0
	v_mov_b32_e32 v62, v0
	v_mov_b32_e32 v63, v0
	v_mov_b32_e32 v64, v0
	v_mov_b32_e32 v65, v0
	v_mov_b32_e32 v66, v0
	v_mov_b32_e32 v67, v0
	v_mov_b32_e32 v68, v0
	v_mov_b32_e32 v69, v0
	v_mov_b32_e32 v70, v0
	v_mov_b32_e32 v71, v0
	v_mov_b32_e32 v80, v0
	v_mov_b32_e32 v81, v0
	v_mov_b32_e32 v82, v0
	v_mov_b32_e32 v83, v0
	v_mov_b32_e32 v84, v0
	v_mov_b32_e32 v85, v0
	v_mov_b32_e32 v86, v0
	v_mov_b32_e32 v87, v0
	v_mov_b32_e32 v96, v0
	v_mov_b32_e32 v97, v0
	v_mov_b32_e32 v98, v0
	v_mov_b32_e32 v99, v0
	v_mov_b32_e32 v100, v0
	v_mov_b32_e32 v101, v0
	v_mov_b32_e32 v102, v0
	v_mov_b32_e32 v103, v0
	v_mov_b32_e32 v112, v0
	v_mov_b32_e32 v113, v0
	v_mov_b32_e32 v114, v0
	v_mov_b32_e32 v115, v0
	v_mov_b32_e32 v116, v0
	v_mov_b32_e32 v117, v0
	v_mov_b32_e32 v118, v0
	v_mov_b32_e32 v119, v0
	v_mov_b32_e32 v72, v0
	v_mov_b32_e32 v73, v0
	v_mov_b32_e32 v74, v0
	v_mov_b32_e32 v75, v0
	v_mov_b32_e32 v76, v0
	v_mov_b32_e32 v77, v0
	v_mov_b32_e32 v78, v0
	v_mov_b32_e32 v79, v0
	v_mov_b32_e32 v88, v0
	v_mov_b32_e32 v89, v0
	v_mov_b32_e32 v90, v0
	v_mov_b32_e32 v91, v0
	v_mov_b32_e32 v92, v0
	v_mov_b32_e32 v93, v0
	v_mov_b32_e32 v94, v0
	v_mov_b32_e32 v95, v0
	v_mov_b32_e32 v104, v0
	v_mov_b32_e32 v105, v0
	v_mov_b32_e32 v106, v0
	v_mov_b32_e32 v107, v0
	v_mov_b32_e32 v108, v0
	v_mov_b32_e32 v109, v0
	v_mov_b32_e32 v110, v0
	v_mov_b32_e32 v111, v0
	v_mov_b32_e32 v120, v0
	v_mov_b32_e32 v121, v0
	v_mov_b32_e32 v122, v0
	v_mov_b32_e32 v123, v0
	v_mov_b32_e32 v124, v0
	v_mov_b32_e32 v125, v0
	v_mov_b32_e32 v126, v0
	v_mov_b32_e32 v127, v0
	s_branch .LBB0_4016
	s_nop 0
	s_nop 0
	s_nop 0
	s_nop 0
	s_nop 0
	s_nop 0
	s_nop 0
	s_nop 0
	s_nop 0
	s_nop 0
	s_nop 0
	s_nop 0
	s_nop 0
	s_nop 0
	s_nop 0
	s_nop 0
	s_nop 0
	s_nop 0
	s_nop 0
	s_nop 0
	s_nop 0
	s_nop 0
	s_nop 0
	s_nop 0
	s_nop 0
	s_nop 0
	s_nop 0
	s_nop 0
	s_nop 0
	s_nop 0
